# phase 4 rebalanced: the 192 non-GEMM workgroups take FFN2 weight-transpose items 0..2687 (two passes of their specialised loop), the 64 compress-GEMM workgroups start at item 2688
# speedup vs baseline: 1.0037x; 1.0037x over previous
.LBB0_465:
	s_cmp_gt_i32 s97, 63
	s_mov_b64 s[0:1], -1
	s_cbranch_scc0 .LBB0_491
	s_mov_b32 s48, 0
	s_mov_b32 s49, 0
	s_mov_b32 s32, 0
	s_movk_i32 s96, 0x580
	s_sub_i32 s30, s97, 64
	v_mov_b32_e32 v0, v224
	s_lshl_b32 s29, s30, 3
	s_waitcnt lgkmcnt(0)
	v_ashrrev_i32_e32 v1, 6, v0
	s_sub_i32 s31, s94, 64
	v_add_u32_e32 v4, s29, v1
	s_movk_i32 s0, 0x100
	s_lshl_b32 s28, s31, 3
	v_cmp_gt_i32_e32 vcc, s0, v4
	s_and_saveexec_b64 s[0:1], vcc
	s_cbranch_execz .LBB0_473
	v_and_b32_e32 v5, 63, v0
	v_mbcnt_lo_u32_b32 v0, -1, 0
	v_mbcnt_hi_u32_b32 v0, -1, v0
	v_and_b32_e32 v1, 64, v0
	v_add_u32_e32 v1, 64, v1
	v_xor_b32_e32 v2, 1, v0
	v_cmp_lt_i32_e64 s[2:3], v2, v1
	s_lshl_b32 s6, s94, 12
	s_lshl_b32 s7, s94, 6
	v_cndmask_b32_e64 v2, v0, v2, s[2:3]
	v_lshlrev_b32_e32 v6, 2, v2
	v_xor_b32_e32 v2, 2, v0
	v_cmp_lt_i32_e64 s[2:3], v2, v1
	v_cmp_eq_u32_e32 vcc, 0, v5
	v_lshlrev_b32_e32 v12, 9, v4
	v_cndmask_b32_e64 v2, v0, v2, s[2:3]
	v_lshlrev_b32_e32 v7, 2, v2
	v_xor_b32_e32 v2, 4, v0
	v_cmp_lt_i32_e64 s[2:3], v2, v1
	s_add_i32 s6, s6, 0xfffc0000
	v_lshlrev_b32_e32 v13, 3, v4
	v_cndmask_b32_e64 v2, v0, v2, s[2:3]
	v_lshlrev_b32_e32 v8, 2, v2
	v_xor_b32_e32 v2, 8, v0
	v_cmp_lt_i32_e64 s[2:3], v2, v1
	s_addk_i32 s7, 0xf000
	s_mov_b64 s[4:5], 0
	v_cndmask_b32_e64 v2, v0, v2, s[2:3]
	v_lshlrev_b32_e32 v9, 2, v2
	v_xor_b32_e32 v2, 16, v0
	v_cmp_lt_i32_e64 s[2:3], v2, v1
	s_movk_i32 s8, 0x600
	v_mov_b32_e32 v14, 0x1800
	v_cndmask_b32_e64 v2, v0, v2, s[2:3]
	v_lshlrev_b32_e32 v10, 2, v2
	v_xor_b32_e32 v2, 32, v0
	v_cmp_lt_i32_e64 s[2:3], v2, v1
	v_mov_b32_e32 v15, 0x1600
	s_mov_b32 s9, 0xe00000
	v_cndmask_b32_e64 v0, v0, v2, s[2:3]
	v_lshlrev_b32_e32 v11, 2, v0
	s_movk_i32 s10, 0x80
	v_mov_b32_e32 v1, 0
	s_movk_i32 s11, 0xff
	s_branch .LBB0_469

.LBB0_485:
	v_mov_b32_e32 v0, v224
	s_mov_b32 s0, s96
	v_ashrrev_i32_e32 v1, 6, v0
	v_add_u32_e32 v37, s29, v1
	v_add_u32_e32 v37, s32, v37
	v_cmp_gt_i32_e32 vcc, s0, v37
	s_waitcnt lgkmcnt(0)
	s_barrier
	s_and_saveexec_b64 s[0:1], vcc
	s_cbranch_execz .LBB0_490
	s_movk_i32 s2, 0x2100
	v_mul_lo_u32 v1, v1, s2
	v_and_b32_e32 v2, 7, v0
	v_bfe_u32 v39, v0, 3, 3
	v_add_u32_e32 v1, 0, v1
	v_lshlrev_b32_e32 v0, 4, v2
	v_mul_u32_u24_e32 v2, 0x420, v2
	v_lshlrev_b32_e32 v5, 2, v39
	s_cmp_lg_u64 s[20:21], 0
	v_readlane_b32 s52, v245, 33
	v_add_u32_e32 v3, v1, v0
	v_add3_u32 v49, v1, v2, v5
	v_mov_b32_e32 v1, 0
	s_cselect_b64 s[2:3], -1, 0
	v_readlane_b32 s60, v245, 41
	v_readlane_b32 s61, v245, 42
	v_mul_u32_u24_e32 v4, 0x84, v39
	v_lshl_add_u64 v[32:33], s[22:23], 0, v[0:1]
	v_lshl_add_u64 v[34:35], s[60:61], 0, v[0:1]
	v_lshl_add_u64 v[34:35], v[34:35], 0, s[48:49]
	v_cndmask_b32_e64 v0, 0, 1, s[2:3]
	v_or_b32_e32 v46, 8, v39
	v_or_b32_e32 v47, 16, v39
	v_or_b32_e32 v48, 24, v39
	s_mov_b64 s[4:5], 0
	v_lshlrev_b32_e32 v36, 5, v37
	s_lshl_b32 s6, s28, 5
	v_lshlrev_b32_e32 v38, 6, v37
	s_lshl_b32 s7, s28, 6
	s_mov_b32 s8, 0x2e8ba2e9
	s_movk_i32 s9, 0xf500
	s_movk_i32 s10, 0x2c00
	v_cmp_ne_u32_e64 s[2:3], 1, v0
	v_add_u32_e32 v50, v3, v4
	s_movk_i32 s11, 0xea00
	s_movk_i32 s12, 0xff00
	s_add_i32 s13, s96, -1
	v_readlane_b32 s53, v245, 34
	v_readlane_b32 s54, v245, 35
	v_readlane_b32 s55, v245, 36
	v_readlane_b32 s56, v245, 37
	v_readlane_b32 s57, v245, 38
	v_readlane_b32 s58, v245, 39
	v_readlane_b32 s59, v245, 40
	v_readlane_b32 s62, v245, 43
	v_readlane_b32 s63, v245, 44
	v_readlane_b32 s64, v245, 45
	v_readlane_b32 s65, v245, 46
	v_readlane_b32 s66, v245, 47
	v_readlane_b32 s67, v245, 48
	s_branch .LBB0_488

.LBB0_490:
	s_or_b64 exec, exec, s[0:1]
	s_cmp_lg_u32 s32, 0
	s_cbranch_scc1 .Lmy_p4b_done
	s_movk_i32 s32, 0x580
	s_movk_i32 s96, 0xa80
	s_mov_b32 s48, 0x3f800
	s_sub_u32 s22, s24, 0xb00000
	s_subb_u32 s23, s25, 0
	s_sub_u32 s20, s20, 0x1000
	s_subb_u32 s21, s21, 0
	s_branch .LBB0_485
.Lmy_p4b_done:
	s_mov_b64 s[0:1], 0
	s_barrier

.LBB0_514:
	v_mov_b32_e32 v0, v224
	s_lshl_b32 s0, s97, 3
	s_waitcnt vmcnt(0)
	s_barrier
	s_addk_i32 s0, 0xa80
	v_ashrrev_i32_e32 v1, 6, v0
	v_add_u32_e32 v49, s0, v1
	s_movk_i32 s0, 0x1280
	v_cmp_gt_i32_e32 vcc, s0, v49
	s_waitcnt vmcnt(0)
	s_barrier
	s_and_saveexec_b64 s[0:1], vcc
	s_cbranch_execz .LBB0_533
	s_movk_i32 s2, 0x2100
	v_mul_lo_u32 v1, v1, s2
	v_and_b32_e32 v2, 7, v0
	v_readlane_b32 s52, v245, 33
	v_add_u32_e32 v1, 0, v1
	v_bfe_u32 v51, v0, 3, 3
	v_lshlrev_b32_e32 v32, 4, v2
	v_readlane_b32 s60, v245, 41
	v_readlane_b32 s61, v245, 42
	v_add_u32_e32 v0, v1, v32
	v_mul_u32_u24_e32 v3, 0x84, v51
	v_mul_u32_u24_e32 v2, 0x420, v2
	v_lshlrev_b32_e32 v4, 2, v51
	v_mov_b32_e32 v33, 0
	v_readlane_b32 s62, v245, 43
	v_readlane_b32 s63, v245, 44
	v_readlane_b32 s66, v245, 47
	v_readlane_b32 s67, v245, 48
	s_mov_b64 s[12:13], s[60:61]
	v_add3_u32 v61, v1, v2, v4
	v_lshl_add_u64 v[34:35], s[18:19], 0, v[32:33]
	s_mov_b64 s[14:15], s[62:63]
	s_mov_b64 s[18:19], s[66:67]
	s_cmp_lg_u64 s[20:21], 0
	v_mov_b32_e32 v1, 0x7fffea00
	v_add_u32_e32 v63, v0, v3
	v_or_b32_e32 v58, 8, v51
	v_or_b32_e32 v59, 16, v51
	v_or_b32_e32 v60, 24, v51
	v_lshl_add_u64 v[36:37], s[18:19], 0, v[32:33]
	v_lshl_add_u64 v[38:39], s[26:27], 0, v[32:33]
	v_lshl_add_u64 v[40:41], s[14:15], 0, v[32:33]
	v_lshl_add_u64 v[42:43], s[24:25], 0, v[32:33]
	v_lshl_add_u64 v[44:45], s[12:13], 0, v[32:33]
	v_lshl_add_u64 v[46:47], s[22:23], 0, v[32:33]
	s_mov_b64 s[2:3], 0
	s_cselect_b64 s[4:5], -1, 0
	v_lshlrev_b32_e32 v48, 5, v49
	v_lshlrev_b32_e32 v50, 6, v49
	v_lshl_add_u32 v62, v49, 1, v1
	s_movk_i32 s12, 0x57f
	s_movk_i32 s13, 0xaff
	s_movk_i32 s14, 0x107f
	s_movk_i32 s15, 0xf500
	v_add_u32_e32 v64, 0x420, v63
	v_add_u32_e32 v65, 0x428, v63
	v_add_u32_e32 v66, 0x840, v63
	v_add_u32_e32 v67, 0x848, v63
	v_add_u32_e32 v68, 0xc60, v63
	v_add_u32_e32 v69, 0xc68, v63
	v_add_u32_e32 v70, 0x1080, v63
	v_add_u32_e32 v71, 0x1088, v63
	v_add_u32_e32 v72, 0x14a0, v63
	v_add_u32_e32 v73, 0x14a8, v63
	v_add_u32_e32 v74, 0x18c0, v63
	v_add_u32_e32 v75, 0x18c8, v63
	v_add_u32_e32 v76, 0x1ce0, v63
	v_add_u32_e32 v77, 0x1ce8, v63
	s_mov_b32 s18, 0xffc0
	s_movk_i32 s19, 0x2c00
	s_movk_i32 s22, 0x1f00
	s_mov_b32 s23, 0x40000
	s_mov_b32 s24, 0x2e8ba2e9
	s_movk_i32 s25, 0xea00
	s_movk_i32 s26, 0xff00
	v_mov_b32_e32 v78, 1
	v_readlane_b32 s53, v245, 34
	v_readlane_b32 s54, v245, 35
	v_readlane_b32 s55, v245, 36
	v_readlane_b32 s56, v245, 37
	v_readlane_b32 s57, v245, 38
	v_readlane_b32 s58, v245, 39
	v_readlane_b32 s59, v245, 40
	v_readlane_b32 s64, v245, 45
	v_readlane_b32 s65, v245, 46
	s_branch .LBB0_518
